# batched staging loads for NA, ret_out, SWA item loops
# speedup vs baseline: 1.0118x; 1.0118x over previous
.LBB0_680:
	s_and_b32 s4, s22, 1
	s_lshl_b32 s5, s22, 6
	s_and_b32 s6, s5, 0xffffff80
	s_cmp_lt_i32 s6, 0x10000
	s_movk_i32 s7, 0xf80
	s_cselect_b32 s7, s7, 0x1f80
	s_movk_i32 s8, 0x2000
	s_cselect_b32 s8, 0x1000, s8
	s_and_b32 s7, s7, s5
	v_lshrrev_b32_e32 v0, 3, v195
	v_bfe_u32 v1, v195, 2, 1
	v_and_b32_e32 v2, 3, v195
	v_lshlrev_b32_e32 v3, 6, v1
	v_lshl_or_b32 v3, v2, 4, v3
	v_mul_u32_u24_e32 v4, 0x28000, v0
	v_add_u32_e32 v146, v4, v3
	v_lshrrev_b32_e32 v4, 1, v3
	v_mul_u32_u24_e32 v4, 0x88, v4
	v_lshl_add_u32 v147, v0, 1, v4
	v_and_b32_e32 v4, 35, v0
	v_bfe_u32 v5, v0, 2, 1
	v_lshl_or_b32 v4, v5, 4, v4
	v_bfe_u32 v5, v0, 3, 2
	v_lshl_or_b32 v4, v5, 2, v4
	v_mul_u32_u24_e32 v4, 0x310, v4
	v_add_u32_e32 v206, v4, v3
	s_lshl_b32 s9, s6, 1
	s_mul_i32 s10, s4, 0xa00000
	s_add_u32 s9, s9, s10
	v_readlane_b32 s10, v254, 9
	v_readlane_b32 s11, v254, 10
	s_add_u32 s10, s10, s9
	s_addc_u32 s11, s11, 0
	v_readlane_b32 s12, v254, 11
	v_readlane_b32 s13, v254, 12
	s_add_u32 s12, s12, s9
	s_addc_u32 s13, s13, 0
	global_load_dwordx4 v[156:159], v146, s[10:11]
	global_load_dwordx4 v[160:163], v146, s[10:11] offset:128
	global_load_dwordx4 v[180:183], v146, s[12:13]
	global_load_dwordx4 v[184:187], v146, s[12:13] offset:128
	s_cmp_lg_u32 s7, 0
	s_cbranch_scc0 .Lswa_lo_zero
	global_load_dwordx4 v[148:151], v146, s[10:11] offset:-256
	global_load_dwordx4 v[152:155], v146, s[10:11] offset:-128
	global_load_dwordx4 v[172:175], v146, s[12:13] offset:-256
	global_load_dwordx4 v[176:179], v146, s[12:13] offset:-128
	s_branch .Lswa_lo_done
.Lswa_lo_zero:
	v_mov_b32_e32 v148, 0
	v_mov_b32_e32 v149, 0
	v_mov_b32_e32 v150, 0
	v_mov_b32_e32 v151, 0
	v_mov_b32_e32 v152, 0
	v_mov_b32_e32 v153, 0
	v_mov_b32_e32 v154, 0
	v_mov_b32_e32 v155, 0
	v_mov_b32_e32 v172, 0
	v_mov_b32_e32 v173, 0
	v_mov_b32_e32 v174, 0
	v_mov_b32_e32 v175, 0
	v_mov_b32_e32 v176, 0
	v_mov_b32_e32 v177, 0
	v_mov_b32_e32 v178, 0
	v_mov_b32_e32 v179, 0
.Lswa_lo_done:
	s_add_i32 s9, s7, 0x80
	s_cmp_lt_i32 s9, s8
	s_cbranch_scc0 .Lswa_hi_zero
	global_load_dwordx4 v[164:167], v146, s[10:11] offset:256
	global_load_dwordx4 v[168:171], v146, s[10:11] offset:384
	global_load_dwordx4 v[188:191], v146, s[12:13] offset:256
	global_load_dwordx4 v[208:211], v146, s[12:13] offset:384
	s_branch .Lswa_hi_done
.Lswa_hi_zero:
	v_mov_b32_e32 v164, 0
	v_mov_b32_e32 v165, 0
	v_mov_b32_e32 v166, 0
	v_mov_b32_e32 v167, 0
	v_mov_b32_e32 v168, 0
	v_mov_b32_e32 v169, 0
	v_mov_b32_e32 v170, 0
	v_mov_b32_e32 v171, 0
	v_mov_b32_e32 v188, 0
	v_mov_b32_e32 v189, 0
	v_mov_b32_e32 v190, 0
	v_mov_b32_e32 v191, 0
	v_mov_b32_e32 v208, 0
	v_mov_b32_e32 v209, 0
	v_mov_b32_e32 v210, 0
	v_mov_b32_e32 v211, 0

.LBB0_690:
	s_or_b64 exec, exec, s[2:3]
	s_lshl_b32 s2, s22, 6
	s_and_b32 s15, s2, 0xffffff80
	s_cmp_lt_i32 s15, 0x10000
	s_movk_i32 s3, 0xf80
	s_cselect_b32 s3, s3, 0x1f80
	s_movk_i32 s4, 0x2000
	s_cselect_b32 s12, 0x1000, s4
	s_and_b32 s13, s3, s2
	s_add_i32 s14, s13, 0xffffff80
	s_mov_b64 s[2:3], exec
	s_waitcnt vmcnt(0)
	ds_write_b16 v147, v148 offset:0
	ds_write_b16_d16_hi v147, v148 offset:136
	ds_write_b16 v147, v149 offset:272
	ds_write_b16_d16_hi v147, v149 offset:408
	ds_write_b16 v147, v150 offset:544
	ds_write_b16_d16_hi v147, v150 offset:680
	ds_write_b16 v147, v151 offset:816
	ds_write_b16_d16_hi v147, v151 offset:952
	ds_write_b16 v147, v152 offset:8704
	ds_write_b16_d16_hi v147, v152 offset:8840
	ds_write_b16 v147, v153 offset:8976
	ds_write_b16_d16_hi v147, v153 offset:9112
	ds_write_b16 v147, v154 offset:9248
	ds_write_b16_d16_hi v147, v154 offset:9384
	ds_write_b16 v147, v155 offset:9520
	ds_write_b16_d16_hi v147, v155 offset:9656
	ds_write_b16 v147, v156 offset:17408
	ds_write_b16_d16_hi v147, v156 offset:17544
	ds_write_b16 v147, v157 offset:17680
	ds_write_b16_d16_hi v147, v157 offset:17816
	ds_write_b16 v147, v158 offset:17952
	ds_write_b16_d16_hi v147, v158 offset:18088
	ds_write_b16 v147, v159 offset:18224
	ds_write_b16_d16_hi v147, v159 offset:18360
	ds_write_b16 v147, v160 offset:26112
	ds_write_b16_d16_hi v147, v160 offset:26248
	ds_write_b16 v147, v161 offset:26384
	ds_write_b16_d16_hi v147, v161 offset:26520
	ds_write_b16 v147, v162 offset:26656
	ds_write_b16_d16_hi v147, v162 offset:26792
	ds_write_b16 v147, v163 offset:26928
	ds_write_b16_d16_hi v147, v163 offset:27064
	ds_write_b16 v147, v164 offset:34816
	ds_write_b16_d16_hi v147, v164 offset:34952
	ds_write_b16 v147, v165 offset:35088
	ds_write_b16_d16_hi v147, v165 offset:35224
	ds_write_b16 v147, v166 offset:35360
	ds_write_b16_d16_hi v147, v166 offset:35496
	ds_write_b16 v147, v167 offset:35632
	ds_write_b16_d16_hi v147, v167 offset:35768
	ds_write_b16 v147, v168 offset:43520
	ds_write_b16_d16_hi v147, v168 offset:43656
	ds_write_b16 v147, v169 offset:43792
	ds_write_b16_d16_hi v147, v169 offset:43928
	ds_write_b16 v147, v170 offset:44064
	ds_write_b16_d16_hi v147, v170 offset:44200
	ds_write_b16 v147, v171 offset:44336
	ds_write_b16_d16_hi v147, v171 offset:44472
	ds_write_b128 v206, v[172:175] offset:52224
	ds_write_b128 v206, v[176:179] offset:52352
	ds_write_b128 v206, v[180:183] offset:52480
	ds_write_b128 v206, v[184:187] offset:52608
	ds_write_b128 v206, v[188:191] offset:52736
	ds_write_b128 v206, v[208:211] offset:52864

.Lro_compute:
	s_or_b32 s0, s14, s22
	s_lshl_b64 s[2:3], s[0:1], 2
	s_add_u32 s2, s48, s2
	s_addc_u32 s3, s49, s3
	s_waitcnt lgkmcnt(0)
	s_barrier
	global_load_dword v2, v193, s[2:3]
	global_load_dword v3, v193, s[2:3] offset:16
	s_mov_b32 s0, 0xbfb8aa3b
	s_mov_b32 s2, 0x42ce8ed0
	s_mov_b32 s3, 0x33800000
	v_add_u32_e32 v34, vcc_lo, v38
	v_ashrrev_i32_e32 v35, 31, v34
	v_lshlrev_b64 v[36:37], 9, v[34:35]
	v_lshlrev_b32_e32 v192, 1, v32
	v_lshlrev_b64 v[34:35], 11, v[34:35]
	s_waitcnt vmcnt(1)
	v_mul_f32_e32 v4, 0xbfb8aa3b, v2
	v_fma_f32 v5, v2, s0, -v4
	v_rndne_f32_e32 v6, v4
	v_fmac_f32_e32 v5, 0xb2a5705f, v2
	v_sub_f32_e32 v4, v4, v6
	v_add_f32_e32 v4, v4, v5
	v_cvt_i32_f32_e32 v6, v6
	v_exp_f32_e32 v4, v4
	s_waitcnt vmcnt(0)
	v_mul_f32_e32 v5, 0xbfb8aa3b, v3
	v_rndne_f32_e32 v7, v5
	v_cmp_nlt_f32_e64 s[68:69], s2, v2
	v_ldexp_f32 v4, v4, v6
	v_fma_f32 v6, v3, s0, -v5
	v_fmac_f32_e32 v6, 0xb2a5705f, v3
	v_sub_f32_e32 v5, v5, v7
	v_add_f32_e32 v5, v5, v6
	v_cvt_i32_f32_e32 v7, v7
	v_exp_f32_e32 v5, v5
	v_cndmask_b32_e64 v4, 0, v4, s[68:69]
	v_cmp_nlt_f32_e64 s[68:69], s2, v3
	s_mov_b32 s0, 0xc2b17218
	v_ldexp_f32 v5, v5, v7
	v_cndmask_b32_e64 v5, 0, v5, s[68:69]
	v_cmp_ngt_f32_e64 s[68:69], s0, v2
	s_mov_b32 s2, 0x3f317218
	s_nop 0
	v_cndmask_b32_e64 v18, v224, v4, s[68:69]
	v_cmp_ngt_f32_e64 s[68:69], s0, v3
	v_add_f32_e32 v4, 1.0, v18
	v_cvt_f64_f32_e32 v[2:3], v4
	v_cndmask_b32_e64 v19, v224, v5, s[68:69]
	v_frexp_mant_f32_e32 v5, v4
	s_mov_b32 s0, 0x3f2aaaab
	v_frexp_exp_i32_f64_e32 v2, v[2:3]
	v_cmp_gt_f32_e64 s[68:69], s0, v5
	v_add_f32_e32 v20, 1.0, v19
	v_frexp_mant_f32_e32 v6, v20
	v_subbrev_co_u32_e64 v5, s[68:69], 0, v2, s[68:69]
	v_cvt_f64_f32_e32 v[2:3], v20
	v_frexp_exp_i32_f64_e32 v2, v[2:3]
	v_cmp_gt_f32_e64 s[68:69], s0, v6
	v_sub_u32_e32 v6, 0, v5
	s_mov_b32 s0, 0x7f800000
	v_subbrev_co_u32_e64 v21, s[68:69], 0, v2, s[68:69]
	v_add_f32_e32 v2, -1.0, v4
	v_sub_f32_e32 v3, v2, v4
	v_sub_f32_e32 v2, v18, v2
	v_add_f32_e32 v3, 1.0, v3
	v_add_f32_e32 v3, v2, v3
	v_ldexp_f32 v4, v4, v6
	v_ldexp_f32 v3, v3, v6
	v_add_f32_e32 v6, -1.0, v4
	v_add_f32_e32 v7, 1.0, v4
	v_cvt_f32_i32_e32 v2, v5
	v_add_f32_e32 v5, 1.0, v6
	v_add_f32_e32 v8, -1.0, v7
	v_sub_f32_e32 v5, v4, v5
	v_sub_f32_e32 v4, v4, v8
	v_add_f32_e32 v8, v3, v5
	v_add_f32_e32 v3, v3, v4
	v_add_f32_e32 v10, v7, v3
	v_rcp_f32_e32 v11, v10
	v_add_f32_e32 v5, v6, v8
	v_sub_f32_e32 v6, v6, v5
	v_sub_f32_e32 v4, v7, v10
	v_mul_f32_e32 v13, v5, v11
	v_add_f32_e32 v12, v8, v6
	v_mul_f32_e32 v6, v10, v13
	v_add_f32_e32 v3, v3, v4
	v_fma_f32 v8, v13, v10, -v6
	v_fmac_f32_e32 v8, v13, v3
	v_add_f32_e32 v4, v6, v8
	v_sub_f32_e32 v7, v5, v4
	v_mov_b32_e32 v9, v4
	v_pk_add_f32 v[4:5], v[4:5], v[6:7] neg_lo:[0,1] neg_hi:[0,1]
	v_cmp_neq_f32_e64 s[68:69], s0, v18
	v_pk_add_f32 v[4:5], v[4:5], v[8:9] neg_lo:[0,1] neg_hi:[0,1]
	s_nop 0
	v_add_f32_e32 v5, v12, v5
	v_add_f32_e32 v4, v4, v5
	v_add_f32_e32 v5, v7, v4
	v_mul_f32_e32 v9, v11, v5
	v_mul_f32_e32 v6, v10, v9
	v_sub_f32_e32 v7, v7, v5
	v_add_f32_e32 v14, v13, v9
	v_fma_f32 v8, v9, v10, -v6
	v_add_f32_e32 v12, v4, v7
	v_sub_f32_e32 v4, v14, v13
	v_fmac_f32_e32 v8, v9, v3
	v_sub_f32_e32 v3, v9, v4
	v_add_f32_e32 v4, v6, v8
	v_sub_f32_e32 v7, v5, v4
	v_mov_b32_e32 v9, v4
	v_pk_add_f32 v[4:5], v[4:5], v[6:7] neg_lo:[0,1] neg_hi:[0,1]
	s_nop 0
	v_pk_add_f32 v[4:5], v[4:5], v[8:9] neg_lo:[0,1] neg_hi:[0,1]
	s_nop 0
	v_add_f32_e32 v5, v12, v5
	v_add_f32_e32 v4, v4, v5
	v_add_f32_e32 v4, v7, v4
	v_mul_f32_e32 v4, v11, v4
	v_add_f32_e32 v3, v3, v4
	v_add_f32_e32 v4, v14, v3
	v_mul_f32_e32 v6, v4, v4
	v_sub_f32_e32 v7, v4, v14
	v_fmamk_f32 v8, v6, 0x3e9b6dac, v221
	v_sub_f32_e32 v7, v3, v7
	v_mul_f32_e32 v3, v4, v6
	v_fmaak_f32 v201, v6, v8, 0x3f2aaada
	v_ldexp_f32 v9, v7, 1
	v_pk_mul_f32 v[6:7], v[2:3], v[200:201]
	v_ldexp_f32 v5, v4, 1
	v_fma_f32 v4, v2, s2, -v6
	v_fmac_f32_e32 v4, 0xb102e308, v2
	v_pk_add_f32 v[2:3], v[6:7], v[4:5]
	v_mov_b32_e32 v8, v6
	v_sub_f32_e32 v12, v3, v5
	v_pk_add_f32 v[10:11], v[2:3], v[6:7] neg_lo:[0,1] neg_hi:[0,1]
	v_sub_f32_e32 v7, v7, v12
	v_add_f32_e32 v9, v9, v7
	v_pk_add_f32 v[14:15], v[2:3], v[8:9]
	v_mov_b32_e32 v5, v2
	v_mov_b32_e32 v11, v15
	v_pk_add_f32 v[16:17], v[4:5], v[10:11] neg_lo:[0,1] neg_hi:[0,1]
	v_pk_add_f32 v[4:5], v[4:5], v[10:11]
	v_mov_b32_e32 v6, v3
	v_mov_b32_e32 v13, v2
	v_pk_add_f32 v[2:3], v[4:5], v[2:3] op_sel:[1,0] op_sel_hi:[0,1] neg_lo:[0,1] neg_hi:[0,1]
	v_mov_b32_e32 v12, v9
	v_mov_b32_e32 v8, v15
	v_mov_b32_e32 v9, v5
	v_mov_b32_e32 v7, v2
	v_pk_add_f32 v[10:11], v[14:15], v[2:3] op_sel_hi:[1,0] neg_lo:[0,1] neg_hi:[0,1]
	v_pk_add_f32 v[2:3], v[8:9], v[6:7] neg_lo:[0,1] neg_hi:[0,1]
	v_mov_b32_e32 v10, v16
	v_pk_add_f32 v[2:3], v[12:13], v[2:3] neg_lo:[0,1] neg_hi:[0,1]
	v_mov_b32_e32 v17, v5
	v_pk_add_f32 v[6:7], v[10:11], v[2:3]
	s_nop 0
	v_pk_add_f32 v[8:9], v[6:7], v[6:7] op_sel:[0,1] op_sel_hi:[1,0]
	s_nop 0
	v_pk_add_f32 v[4:5], v[4:5], v[8:9] op_sel:[1,0] op_sel_hi:[0,1]
	v_mov_b32_e32 v7, v4
	v_mov_b32_e32 v3, v8
	v_pk_add_f32 v[8:9], v[6:7], v[16:17] neg_lo:[0,1] neg_hi:[0,1]
	s_nop 0
	v_sub_f32_e32 v5, v6, v8
	v_pk_add_f32 v[2:3], v[2:3], v[8:9] neg_lo:[0,1] neg_hi:[0,1]
	v_sub_f32_e32 v5, v16, v5
	v_add_f32_e32 v2, v2, v5
	v_add_f32_e32 v2, v2, v3
	v_add_f32_e32 v2, v4, v2
	v_cndmask_b32_e64 v2, v224, v2, s[68:69]
	v_cmp_lt_f32_e64 s[68:69], |v18|, s3
	s_nop 1
	v_cndmask_b32_e64 v18, v2, v18, s[68:69]
	v_add_f32_e32 v2, -1.0, v20
	v_sub_f32_e32 v3, v2, v20
	v_sub_f32_e32 v2, v19, v2
	v_add_f32_e32 v3, 1.0, v3
	v_add_f32_e32 v2, v2, v3
	v_sub_u32_e32 v3, 0, v21
	v_ldexp_f32 v4, v20, v3
	v_add_f32_e32 v5, -1.0, v4
	v_ldexp_f32 v2, v2, v3
	v_add_f32_e32 v3, 1.0, v5
	v_sub_f32_e32 v3, v4, v3
	v_add_f32_e32 v6, v2, v3
	v_add_f32_e32 v3, 1.0, v4
	v_add_f32_e32 v7, -1.0, v3
	v_sub_f32_e32 v4, v4, v7
	v_add_f32_e32 v2, v2, v4
	v_add_f32_e32 v10, v3, v2
	v_rcp_f32_e32 v12, v10
	v_sub_f32_e32 v3, v3, v10
	v_add_f32_e32 v11, v2, v3
	v_add_f32_e32 v3, v5, v6
	v_mul_f32_e32 v14, v3, v12
	v_sub_f32_e32 v2, v5, v3
	v_mul_f32_e32 v4, v10, v14
	v_add_f32_e32 v13, v6, v2
	v_fma_f32 v6, v14, v10, -v4
	v_fmac_f32_e32 v6, v14, v11
	v_add_f32_e32 v2, v4, v6
	v_sub_f32_e32 v5, v3, v2
	v_pk_add_f32 v[8:9], v[2:3], v[4:5] neg_lo:[0,1] neg_hi:[0,1]
	v_mov_b32_e32 v7, v2
	v_pk_add_f32 v[2:3], v[8:9], v[6:7] neg_lo:[0,1] neg_hi:[0,1]
	v_cmp_neq_f32_e64 s[68:69], s0, v19
	v_add_f32_e32 v3, v13, v3
	v_add_f32_e32 v2, v2, v3
	v_add_f32_e32 v3, v5, v2
	v_mul_f32_e32 v13, v12, v3
	v_mul_f32_e32 v4, v10, v13
	v_fma_f32 v6, v13, v10, -v4
	v_fmac_f32_e32 v6, v13, v11
	v_sub_f32_e32 v5, v5, v3
	v_add_f32_e32 v10, v2, v5
	v_add_f32_e32 v2, v4, v6
	v_sub_f32_e32 v5, v3, v2
	v_pk_add_f32 v[8:9], v[2:3], v[4:5] neg_lo:[0,1] neg_hi:[0,1]
	v_mov_b32_e32 v7, v2
	v_pk_add_f32 v[2:3], v[8:9], v[6:7] neg_lo:[0,1] neg_hi:[0,1]
	v_mul_f32_e32 v110, 0xbfb8aa3b, v18
	v_add_f32_e32 v3, v10, v3
	v_add_f32_e32 v2, v2, v3
	v_add_f32_e32 v3, v14, v13
	v_add_f32_e32 v2, v5, v2
	v_sub_f32_e32 v4, v3, v14
	v_mul_f32_e32 v2, v12, v2
	v_sub_f32_e32 v4, v13, v4
	v_add_f32_e32 v4, v4, v2
	v_add_f32_e32 v6, v3, v4
	v_mul_f32_e32 v7, v6, v6
	v_fmamk_f32 v2, v7, 0x3e9b6dac, v221
	v_fmaak_f32 v201, v7, v2, 0x3f2aaada
	v_cvt_f32_i32_e32 v2, v21
	v_sub_f32_e32 v3, v6, v3
	v_sub_f32_e32 v3, v4, v3
	v_ldexp_f32 v8, v3, 1
	v_mul_f32_e32 v3, v6, v7
	v_ldexp_f32 v5, v6, 1
	v_pk_mul_f32 v[6:7], v[2:3], v[200:201]
	v_mul_f32_e32 v23, v110, v51
	v_fma_f32 v4, v2, s2, -v6
	v_fmac_f32_e32 v4, 0xb102e308, v2
	v_pk_add_f32 v[2:3], v[6:7], v[4:5]
	v_mul_f32_e32 v27, v110, v67
	v_sub_f32_e32 v5, v3, v5
	v_sub_f32_e32 v5, v7, v5
	v_add_f32_e32 v9, v8, v5
	v_mov_b32_e32 v8, v6
	v_pk_add_f32 v[6:7], v[2:3], v[6:7] neg_lo:[0,1] neg_hi:[0,1]
	v_pk_add_f32 v[10:11], v[2:3], v[8:9]
	v_mov_b32_e32 v5, v2
	v_mov_b32_e32 v7, v11
	v_pk_add_f32 v[12:13], v[4:5], v[6:7] neg_lo:[0,1] neg_hi:[0,1]
	v_pk_add_f32 v[4:5], v[4:5], v[6:7]
	v_mov_b32_e32 v16, v3
	v_pk_add_f32 v[6:7], v[4:5], v[2:3] op_sel:[1,0] op_sel_hi:[0,1] neg_lo:[0,1] neg_hi:[0,1]
	v_pk_add_f32 v[14:15], v[10:11], v[6:7] op_sel_hi:[1,0] neg_lo:[0,1] neg_hi:[0,1]
	v_mov_b32_e32 v10, v11
	v_mov_b32_e32 v11, v5
	v_mov_b32_e32 v17, v6
	v_pk_add_f32 v[6:7], v[10:11], v[16:17] neg_lo:[0,1] neg_hi:[0,1]
	v_mov_b32_e32 v8, v9
	v_mov_b32_e32 v9, v2
	v_pk_add_f32 v[2:3], v[8:9], v[6:7] neg_lo:[0,1] neg_hi:[0,1]
	v_mov_b32_e32 v14, v12
	v_pk_add_f32 v[6:7], v[14:15], v[2:3]
	v_mov_b32_e32 v13, v5
	v_pk_add_f32 v[8:9], v[6:7], v[6:7] op_sel:[0,1] op_sel_hi:[1,0]
	v_mul_f32_e32 v122, v110, v99
	v_pk_add_f32 v[4:5], v[4:5], v[8:9] op_sel:[1,0] op_sel_hi:[0,1]
	v_mov_b32_e32 v7, v4
	v_pk_add_f32 v[10:11], v[6:7], v[12:13] neg_lo:[0,1] neg_hi:[0,1]
	v_mov_b32_e32 v3, v8
	v_sub_f32_e32 v5, v6, v10
	v_pk_add_f32 v[2:3], v[2:3], v[10:11] neg_lo:[0,1] neg_hi:[0,1]
	v_sub_f32_e32 v5, v12, v5
	v_add_f32_e32 v2, v2, v5
	v_add_f32_e32 v2, v2, v3
	v_add_f32_e32 v2, v4, v2
	v_cndmask_b32_e64 v2, v224, v2, s[68:69]
	v_cmp_lt_f32_e64 s[68:69], |v19|, s3
	v_readlane_b32 s2, v254, 15
	v_readlane_b32 s3, v254, 16
	v_cndmask_b32_e64 v16, v2, v19, s[68:69]
	v_mul_f32_e32 v2, v110, v42
	v_cmp_gt_f32_e64 s[68:69], s96, v2
	v_lshl_add_u64 v[2:3], s[2:3], 0, v[36:37]
	v_lshl_add_u64 v[0:1], v[0:1], 1, v[2:3]
	v_lshl_add_u64 v[0:1], v[0:1], 0, v[192:193]
	global_load_dwordx4 v[4:7], v[0:1], off
	s_nop 0
	global_load_dwordx4 v[0:3], v[0:1], off offset:64
	ds_read2_b64 v[8:11], v39 offset1:1
	ds_read2_b64 v[12:15], v39 offset0:8 offset1:9
	s_waitcnt vmcnt(1) lgkmcnt(1)
	v_mfma_f32_16x16x32_bf16 v[8:11], v[8:11], v[4:7], 0
	v_mul_f32_e32 v113, 0xbfb8aa3b, v16
	v_readlane_b32 s2, v254, 49
	v_readlane_b32 s3, v254, 50
	s_waitcnt vmcnt(0) lgkmcnt(0)
	v_mfma_f32_16x16x32_bf16 v[8:11], v[12:15], v[0:3], v[8:11]
	v_mul_f32_e32 v12, v113, v44
	v_mul_f32_e32 v13, v110, v45
	v_cndmask_b32_e64 v12, v13, v12, s[24:25]
	v_exp_f32_e32 v20, v12
	v_mul_f32_e32 v12, v110, v47
	v_mul_f32_e32 v13, v113, v46
	v_cndmask_b32_e64 v12, v12, v13, s[2:3]
	v_exp_f32_e32 v21, v12
	ds_read2_b64 v[12:15], v39 offset0:68 offset1:69
	v_mul_f32_e32 v16, v113, v43
	v_readlane_b32 s2, v254, 51
	v_cndmask_b32_e64 v111, 0, v225, s[68:69]
	v_cndmask_b32_e64 v112, 0, v226, s[68:69]
	v_cmp_gt_f32_e64 s[68:69], s96, v16
	v_mul_f32_e32 v16, v110, v49
	v_mul_f32_e32 v17, v113, v48
	v_readlane_b32 s3, v254, 52
	v_mul_f32_e32 v24, v113, v50
	v_pk_mul_f32 v[28:29], v[8:9], v[20:21]
	v_cndmask_b32_e64 v16, v16, v17, s[2:3]
	v_exp_f32_e32 v22, v16
	ds_read2_b64 v[16:19], v39 offset0:76 offset1:77
	v_readlane_b32 s2, v254, 53
	v_readlane_b32 s3, v254, 54
	s_waitcnt lgkmcnt(1)
	v_mfma_f32_16x16x32_bf16 v[12:15], v[12:15], v[4:7], 0
	v_mul_f32_e32 v20, v113, v58
	v_cndmask_b32_e64 v23, v23, v24, s[2:3]
	v_exp_f32_e32 v23, v23
	v_readlane_b32 s2, v254, 55
	v_readlane_b32 s3, v254, 56
	v_mul_f32_e32 v21, v113, v64
	v_pk_mul_f32 v[116:117], v[10:11], v[22:23]
	s_waitcnt lgkmcnt(0)
	v_mfma_f32_16x16x32_bf16 v[8:11], v[16:19], v[0:3], v[12:15]
	v_mul_f32_e32 v30, v113, v66
	v_mul_f32_e32 v144, v110, v101
	v_mul_f32_e32 v145, v113, v100
	v_mul_f32_e32 v12, v110, v53
	v_mul_f32_e32 v13, v113, v52
	v_cndmask_b32_e64 v12, v12, v13, s[2:3]
	v_readlane_b32 s2, v254, 57
	v_exp_f32_e32 v16, v12
	v_mul_f32_e32 v12, v110, v55
	v_mul_f32_e32 v13, v113, v54
	v_readlane_b32 s3, v254, 58
	v_cndmask_b32_e64 v114, 0, v225, s[68:69]
	v_cndmask_b32_e64 v115, 0, v226, s[68:69]
	v_cndmask_b32_e64 v12, v12, v13, s[2:3]
	v_exp_f32_e32 v17, v12
	v_add_u32_e32 v12, 0x1100, v39
	ds_read2_b64 v[12:15], v12 offset1:1
	v_readlane_b32 s2, v254, 59
	v_pk_mul_f32 v[118:119], v[8:9], v[16:17]
	v_add_u32_e32 v9, 0x1140, v39
	ds_read2_b64 v[16:19], v9 offset1:1
	v_mul_f32_e32 v8, v110, v57
	v_mul_f32_e32 v9, v113, v56
	v_readlane_b32 s3, v254, 60
	s_waitcnt lgkmcnt(1)
	v_mfma_f32_16x16x32_bf16 v[12:15], v[12:15], v[4:7], 0
	v_cndmask_b32_e64 v8, v8, v9, s[2:3]
	v_readlane_b32 s2, v254, 61
	v_mul_f32_e32 v9, v110, v59
	v_readlane_b32 s3, v254, 62
	s_waitcnt lgkmcnt(0)
	v_mfma_f32_16x16x32_bf16 v[12:15], v[16:19], v[0:3], v[12:15]
	v_mul_f32_e32 v16, v110, v61
	v_cndmask_b32_e64 v9, v9, v20, s[2:3]
	v_readlane_b32 s2, v254, 63
	v_mul_f32_e32 v17, v113, v60
	v_readlane_b32 s3, v255, 0
	v_mul_f32_e32 v20, v110, v65
	v_exp_f32_e32 v8, v8
	v_cndmask_b32_e64 v16, v16, v17, s[2:3]
	v_readlane_b32 s2, v255, 1
	v_exp_f32_e32 v24, v16
	v_mul_f32_e32 v16, v110, v63
	v_mul_f32_e32 v17, v113, v62
	v_readlane_b32 s3, v255, 2
	v_exp_f32_e32 v9, v9
	v_fmac_f32_e32 v111, v110, v42
	v_cndmask_b32_e64 v16, v16, v17, s[2:3]
	v_exp_f32_e32 v25, v16
	v_add_u32_e32 v16, 0x1320, v39
	ds_read2_b64 v[16:19], v16 offset1:1
	v_readlane_b32 s2, v255, 3
	v_readlane_b32 s3, v255, 4
	v_pk_mul_f32 v[124:125], v[12:13], v[24:25]
	v_mul_f32_e32 v12, v110, v69
	v_cndmask_b32_e64 v20, v20, v21, s[2:3]
	v_exp_f32_e32 v26, v20
	v_add_u32_e32 v20, 0x1360, v39
	ds_read2_b64 v[20:23], v20 offset1:1
	v_readlane_b32 s2, v255, 5
	s_waitcnt lgkmcnt(1)
	v_mfma_f32_16x16x32_bf16 v[16:19], v[16:19], v[4:7], 0
	v_readlane_b32 s3, v255, 6
	v_mul_f32_e32 v13, v113, v68
	v_cndmask_b32_e64 v12, v12, v13, s[26:27]
	v_cndmask_b32_e64 v27, v27, v30, s[2:3]
	v_exp_f32_e32 v27, v27
	v_pk_mul_f32 v[120:121], v[10:11], v[8:9]
	s_waitcnt lgkmcnt(0)
	v_mfma_f32_16x16x32_bf16 v[8:11], v[20:23], v[0:3], v[16:19]
	v_mul_f32_e32 v13, v113, v70
	v_pk_mul_f32 v[126:127], v[14:15], v[26:27]
	v_mul_f32_e32 v20, v113, v74
	v_exp_f32_e32 v16, v12
	v_mul_f32_e32 v12, v110, v71
	v_cndmask_b32_e64 v12, v12, v13, s[28:29]
	v_exp_f32_e32 v17, v12
	v_add_u32_e32 v12, 0x2200, v39
	ds_read2_b64 v[12:15], v12 offset1:1
	v_mul_f32_e32 v21, v113, v80
	v_pk_mul_f32 v[128:129], v[8:9], v[16:17]
	v_add_u32_e32 v9, 0x2240, v39
	ds_read2_b64 v[16:19], v9 offset1:1
	s_waitcnt lgkmcnt(1)
	v_mfma_f32_16x16x32_bf16 v[12:15], v[12:15], v[4:7], 0
	v_mul_f32_e32 v8, v110, v73
	v_mul_f32_e32 v9, v113, v72
	s_waitcnt lgkmcnt(0)
	v_mfma_f32_16x16x32_bf16 v[12:15], v[16:19], v[0:3], v[12:15]
	v_mul_f32_e32 v16, v110, v77
	v_mul_f32_e32 v17, v113, v76
	v_cndmask_b32_e64 v16, v16, v17, s[36:37]
	v_exp_f32_e32 v24, v16
	v_mul_f32_e32 v16, v110, v79
	v_mul_f32_e32 v17, v113, v78
	v_cndmask_b32_e64 v16, v16, v17, s[38:39]
	v_exp_f32_e32 v25, v16
	v_add_u32_e32 v16, 0x2420, v39
	v_cndmask_b32_e64 v8, v8, v9, s[30:31]
	v_mul_f32_e32 v9, v110, v75
	ds_read2_b64 v[16:19], v16 offset1:1
	v_cndmask_b32_e64 v9, v9, v20, s[34:35]
	v_mul_f32_e32 v20, v110, v81
	v_cndmask_b32_e64 v20, v20, v21, s[40:41]
	v_exp_f32_e32 v26, v20
	v_add_u32_e32 v20, 0x2460, v39
	ds_read2_b64 v[20:23], v20 offset1:1
	v_exp_f32_e32 v8, v8
	v_exp_f32_e32 v9, v9
	s_waitcnt lgkmcnt(1)
	v_mfma_f32_16x16x32_bf16 v[16:19], v[16:19], v[4:7], 0
	v_mul_f32_e32 v27, v110, v83
	v_mul_f32_e32 v30, v113, v82
	v_cndmask_b32_e64 v27, v27, v30, s[42:43]
	v_pk_mul_f32 v[132:133], v[12:13], v[24:25]
	v_mul_f32_e32 v12, v110, v85
	v_mul_f32_e32 v13, v113, v84
	v_exp_f32_e32 v27, v27
	v_cndmask_b32_e64 v12, v12, v13, s[44:45]
	v_pk_mul_f32 v[130:131], v[10:11], v[8:9]
	s_waitcnt lgkmcnt(0)
	v_mfma_f32_16x16x32_bf16 v[8:11], v[20:23], v[0:3], v[16:19]
	v_mul_f32_e32 v13, v113, v86
	v_pk_mul_f32 v[134:135], v[14:15], v[26:27]
	v_mul_f32_e32 v20, v113, v90
	v_exp_f32_e32 v16, v12
	v_mul_f32_e32 v12, v110, v87
	v_cndmask_b32_e64 v12, v12, v13, s[46:47]
	v_exp_f32_e32 v17, v12
	v_add_u32_e32 v12, 0x3300, v39
	ds_read2_b64 v[12:15], v12 offset1:1
	v_mul_f32_e32 v21, v113, v94
	v_pk_mul_f32 v[136:137], v[8:9], v[16:17]
	v_add_u32_e32 v9, 0x3340, v39
	ds_read2_b64 v[16:19], v9 offset1:1
	s_waitcnt lgkmcnt(1)
	v_mfma_f32_16x16x32_bf16 v[12:15], v[12:15], v[4:7], 0
	v_mul_f32_e32 v8, v110, v89
	v_mul_f32_e32 v9, v113, v88
	s_waitcnt lgkmcnt(0)
	v_mfma_f32_16x16x32_bf16 v[12:15], v[16:19], v[0:3], v[12:15]
	v_mul_f32_e32 v16, v110, v93
	v_mul_f32_e32 v17, v113, v92
	v_cndmask_b32_e64 v16, v16, v17, s[76:77]
	v_exp_f32_e32 v138, v16
	v_add_u32_e32 v16, 0x3520, v39
	v_cndmask_b32_e64 v8, v8, v9, s[70:71]
	v_mul_f32_e32 v9, v110, v91
	ds_read2_b64 v[16:19], v16 offset1:1
	v_cndmask_b32_e64 v9, v9, v20, s[74:75]
	v_mul_f32_e32 v20, v110, v95
	v_cndmask_b32_e64 v20, v20, v21, s[78:79]
	v_exp_f32_e32 v139, v20
	v_add_u32_e32 v20, 0x3560, v39
	ds_read2_b64 v[20:23], v20 offset1:1
	s_waitcnt lgkmcnt(1)
	v_mfma_f32_16x16x32_bf16 v[16:19], v[16:19], v[4:7], 0
	v_mul_f32_e32 v24, v110, v97
	v_mul_f32_e32 v25, v113, v96
	v_cndmask_b32_e64 v30, v24, v25, s[80:81]
	s_waitcnt lgkmcnt(0)
	v_mfma_f32_16x16x32_bf16 v[20:23], v[20:23], v[0:3], v[16:19]
	ds_read_b128 v[24:27], v40 offset:17408
	s_nop 1
	v_cvt_pk_bf16_f32 v19, v120, v121
	v_mul_f32_e32 v120, v113, v98
	v_cndmask_b32_e64 v120, v122, v120, s[82:83]
	v_exp_f32_e32 v140, v30
	v_cvt_pk_bf16_f32 v16, v28, v29
	ds_read_b128 v[28:31], v40 offset:21760
	v_cvt_pk_bf16_f32 v17, v116, v117
	v_cvt_pk_bf16_f32 v18, v118, v119
	ds_read_b128 v[116:119], v40 offset:26112
	v_exp_f32_e32 v141, v120
	ds_read_b128 v[120:123], v40 offset:30464
	v_exp_f32_e32 v8, v8
	v_exp_f32_e32 v9, v9
	v_pk_mul_f32 v[138:139], v[12:13], v[138:139]
	v_pk_mul_f32 v[140:141], v[14:15], v[140:141]
	ds_read_b128 v[12:15], v40 offset:17472
	s_waitcnt lgkmcnt(4)
	v_mfma_f32_16x16x32_bf16 v[24:27], v[24:27], v[16:19], 0
	v_mul_f32_e64 v142, v10, v8
	v_mul_f32_e64 v143, v11, v9
	v_fmac_f32_e32 v114, v113, v43
	s_mov_b32 s0, 0x800000
	s_waitcnt lgkmcnt(3)
	v_mfma_f32_16x16x32_bf16 v[28:31], v[28:31], v[16:19], 0
	v_readlane_b32 s2, v254, 19
	v_or_b32_e32 v192, v109, v32
	v_readlane_b32 s3, v254, 20
	s_waitcnt lgkmcnt(2)
	v_mfma_f32_16x16x32_bf16 v[8:11], v[116:119], v[16:19], 0
	v_cvt_pk_bf16_f32 v116, v124, v125
	v_cvt_pk_bf16_f32 v117, v126, v127
	v_cvt_pk_bf16_f32 v118, v128, v129
	s_waitcnt lgkmcnt(1)
	v_mfma_f32_16x16x32_bf16 v[16:19], v[120:123], v[16:19], 0
	ds_read_b128 v[120:123], v40 offset:21824
	v_cvt_pk_bf16_f32 v119, v130, v131
	v_cndmask_b32_e64 v124, v144, v145, s[88:89]
	v_exp_f32_e32 v128, v124
	s_waitcnt lgkmcnt(1)
	v_mfma_f32_16x16x32_bf16 v[12:15], v[12:15], v[116:119], v[24:27]
	v_mul_f32_e32 v124, v110, v103
	v_mul_f32_e32 v125, v113, v102
	v_cndmask_b32_e64 v124, v124, v125, s[90:91]
	ds_read_b128 v[24:27], v40 offset:26176
	s_waitcnt lgkmcnt(1)
	v_mfma_f32_16x16x32_bf16 v[28:31], v[120:123], v[116:119], v[28:31]
	ds_read_b128 v[120:123], v40 offset:30528
	v_mul_f32_e32 v130, v110, v105
	s_waitcnt lgkmcnt(1)
	v_mfma_f32_16x16x32_bf16 v[8:11], v[24:27], v[116:119], v[8:11]
	ds_read_b128 v[24:27], v40 offset:17536
	v_mul_f32_e32 v131, v113, v104
	v_exp_f32_e32 v129, v124
	s_waitcnt lgkmcnt(1)
	v_mfma_f32_16x16x32_bf16 v[116:119], v[120:123], v[116:119], v[16:19]
	v_cvt_pk_bf16_f32 v120, v132, v133
	v_cvt_pk_bf16_f32 v121, v134, v135
	v_cvt_pk_bf16_f32 v122, v136, v137
	ds_read_b128 v[16:19], v40 offset:21888
	v_cvt_pk_bf16_f32 v123, v142, v143
	s_waitcnt lgkmcnt(1)
	s_nop 0
	v_mfma_f32_16x16x32_bf16 v[124:127], v[24:27], v[120:123], v[12:15]
	ds_read_b128 v[24:27], v40 offset:26240
	s_nop 1
	v_cndmask_b32_e64 v12, v130, v131, s[64:65]
	v_exp_f32_e32 v130, v12
	s_waitcnt lgkmcnt(1)
	v_mfma_f32_16x16x32_bf16 v[12:15], v[16:19], v[120:123], v[28:31]
	v_mul_f32_e32 v131, v110, v107
	v_mul_f32_e32 v16, v113, v106
	v_cndmask_b32_e64 v16, v131, v16, s[66:67]
	ds_read_b128 v[28:31], v40 offset:30592
	v_exp_f32_e32 v131, v16
	s_waitcnt lgkmcnt(1)
	v_mfma_f32_16x16x32_bf16 v[16:19], v[24:27], v[120:123], v[8:11]
	v_mul_f32_e64 v26, v20, v128
	v_mul_f32_e64 v27, v21, v129
	v_pk_mul_f32 v[128:129], v[22:23], v[130:131]
	v_cvt_pk_bf16_f32 v24, v138, v139
	ds_read_b128 v[8:11], v40 offset:17600
	s_waitcnt lgkmcnt(1)
	v_mfma_f32_16x16x32_bf16 v[20:23], v[28:31], v[120:123], v[116:119]
	ds_read_b128 v[28:31], v40 offset:21952
	v_cvt_pk_bf16_f32 v25, v140, v141
	s_nop 0
	v_add_u32_e32 v116, 64, v242
	v_cvt_pk_bf16_f32 v26, v26, v27
	v_cvt_pk_bf16_f32 v27, v128, v129
	v_cmp_lt_i32_e64 s[68:69], v237, v116
	v_exp_f32_e32 v110, v111
	s_waitcnt lgkmcnt(0)
	v_mfma_f32_16x16x32_bf16 v[12:15], v[28:31], v[24:27], v[12:15]
	v_cndmask_b32_e64 v144, v220, v237, s[68:69]
	v_cmp_lt_i32_e64 s[68:69], v236, v116
	ds_read_b128 v[28:31], v40 offset:26304
	ds_read_b128 v[116:119], v40 offset:30656
	s_waitcnt lgkmcnt(1)
	v_mfma_f32_16x16x32_bf16 v[16:19], v[28:31], v[24:27], v[16:19]
	ds_read_b128 v[28:31], v41 offset:34816
	ds_read_b128 v[120:123], v41 offset:37120
	ds_read_b128 v[128:131], v41 offset:39424
	v_mfma_f32_16x16x32_bf16 v[8:11], v[8:11], v[24:27], v[124:127]
	ds_read_b128 v[132:135], v41 offset:48640
	ds_read_b128 v[136:139], v41 offset:41728
	ds_read_b128 v[140:143], v41 offset:50944
	s_waitcnt lgkmcnt(6)
	v_mfma_f32_16x16x32_bf16 v[20:23], v[116:119], v[24:27], v[20:23]
	ds_read_b128 v[24:27], v41 offset:34880
	ds_read_b128 v[116:119], v41 offset:44032
	ds_read_b128 v[124:127], v41 offset:46336
	s_waitcnt lgkmcnt(8)
	v_mfma_f32_16x16x32_bf16 v[28:31], v[28:31], v[4:7], 0
	v_exp_f32_e32 v111, v114
	v_cndmask_b32_e64 v145, v220, v236, s[68:69]
	s_waitcnt lgkmcnt(2)
	v_mfma_f32_16x16x32_bf16 v[24:27], v[24:27], v[0:3], v[28:31]
	s_nop 3
	ds_read_b128 v[28:31], v41 offset:44096
	s_waitcnt lgkmcnt(2)
	v_mfma_f32_16x16x32_bf16 v[116:119], v[116:119], v[4:7], 0
	s_waitcnt lgkmcnt(0)
	v_mfma_f32_16x16x32_bf16 v[28:31], v[28:31], v[0:3], v[116:119]
	s_nop 5
	ds_read_b128 v[116:119], v41 offset:37184
	v_mfma_f32_16x16x32_bf16 v[120:123], v[120:123], v[4:7], 0
	s_waitcnt lgkmcnt(0)
	v_mfma_f32_16x16x32_bf16 v[116:119], v[116:119], v[0:3], v[120:123]
	s_nop 5
	ds_read_b128 v[120:123], v41 offset:46400
	v_mfma_f32_16x16x32_bf16 v[124:127], v[124:127], v[4:7], 0
	s_waitcnt lgkmcnt(0)
	v_mfma_f32_16x16x32_bf16 v[120:123], v[120:123], v[0:3], v[124:127]
	s_nop 5
	ds_read_b128 v[124:127], v41 offset:39488
	v_mfma_f32_16x16x32_bf16 v[128:131], v[128:131], v[4:7], 0
	s_waitcnt lgkmcnt(0)
	v_mfma_f32_16x16x32_bf16 v[124:127], v[124:127], v[0:3], v[128:131]
	s_nop 5
	ds_read_b128 v[128:131], v41 offset:48704
	v_mfma_f32_16x16x32_bf16 v[132:135], v[132:135], v[4:7], 0
	s_waitcnt lgkmcnt(0)
	v_mfma_f32_16x16x32_bf16 v[128:131], v[128:131], v[0:3], v[132:135]
	s_nop 5
	ds_read_b128 v[132:135], v41 offset:41792
	v_mfma_f32_16x16x32_bf16 v[136:139], v[136:139], v[4:7], 0
	s_waitcnt lgkmcnt(0)
	v_mfma_f32_16x16x32_bf16 v[132:135], v[132:135], v[0:3], v[136:139]
	s_nop 5
	ds_read_b128 v[136:139], v41 offset:51008
	v_mfma_f32_16x16x32_bf16 v[4:7], v[140:143], v[4:7], 0
	s_waitcnt lgkmcnt(0)
	v_mfma_f32_16x16x32_bf16 v[0:3], v[136:139], v[0:3], v[4:7]
	s_nop 5
	v_ldexp_f32 v6, v111, v115
	v_ldexp_f32 v4, v110, v112
	v_pk_mul_f32 v[110:111], v[6:7], v[128:129] op_sel_hi:[0,1]
	v_pk_mul_f32 v[0:1], v[6:7], v[0:1] op_sel_hi:[0,1]
	v_pk_fma_f32 v[0:1], v[4:5], v[132:133], v[0:1] op_sel_hi:[0,1,1]
	v_pk_add_f32 v[0:1], v[20:21], v[0:1]
	v_pk_mul_f32 v[20:21], v[6:7], v[122:123] op_sel_hi:[0,1]
	v_pk_fma_f32 v[20:21], v[4:5], v[118:119], v[20:21] op_sel_hi:[0,1,1]
	v_pk_add_f32 v[14:15], v[14:15], v[20:21]
	v_pk_mul_f32 v[20:21], v[6:7], v[120:121] op_sel_hi:[0,1]
	v_pk_fma_f32 v[110:111], v[4:5], v[124:125], v[110:111] op_sel_hi:[0,1,1]
	v_pk_fma_f32 v[20:21], v[4:5], v[116:117], v[20:21] op_sel_hi:[0,1,1]
	v_pk_add_f32 v[16:17], v[16:17], v[110:111]
	v_pk_mul_f32 v[110:111], v[6:7], v[130:131] op_sel_hi:[0,1]
	v_pk_mul_f32 v[2:3], v[6:7], v[2:3] op_sel_hi:[0,1]
	v_pk_add_f32 v[12:13], v[12:13], v[20:21]
	v_pk_mul_f32 v[20:21], v[6:7], v[30:31] op_sel_hi:[0,1]
	v_pk_mul_f32 v[6:7], v[6:7], v[28:29] op_sel_hi:[0,1]
	v_pk_fma_f32 v[110:111], v[4:5], v[126:127], v[110:111] op_sel_hi:[0,1,1]
	v_pk_fma_f32 v[2:3], v[4:5], v[134:135], v[2:3] op_sel_hi:[0,1,1]
	v_pk_fma_f32 v[20:21], v[4:5], v[26:27], v[20:21] op_sel_hi:[0,1,1]
	v_pk_fma_f32 v[4:5], v[4:5], v[24:25], v[6:7] op_sel_hi:[0,1,1]
	v_pk_add_f32 v[4:5], v[8:9], v[4:5]
	v_pk_add_f32 v[10:11], v[10:11], v[20:21]
	v_add_f32_e32 v6, 0, v4
	v_add_f32_e32 v6, v5, v6
	v_add_f32_e32 v6, v10, v6
	v_add_f32_e32 v6, v11, v6
	v_add_f32_e32 v6, v6, v12
	v_add_f32_e32 v6, v13, v6
	v_add_f32_e32 v6, v14, v6
	v_add_f32_e32 v6, v15, v6
	v_add_f32_e32 v6, v6, v16
	v_pk_add_f32 v[18:19], v[18:19], v[110:111]
	v_add_f32_e32 v6, v17, v6
	v_add_f32_e32 v6, v18, v6
	v_add_f32_e32 v6, v19, v6
	v_add_f32_e32 v6, v6, v0
	v_pk_add_f32 v[2:3], v[22:23], v[2:3]
	v_add_f32_e32 v6, v1, v6
	v_add_f32_e32 v6, v2, v6
	v_lshlrev_b32_e32 v110, 2, v144
	v_add_f32_e32 v6, v3, v6
	ds_bpermute_b32 v7, v110, v6
	v_lshlrev_b32_e32 v111, 2, v145
	s_waitcnt lgkmcnt(0)
	v_add_f32_e32 v6, v6, v7
	ds_bpermute_b32 v7, v111, v6
	s_waitcnt lgkmcnt(0)
	v_add_f32_e32 v6, v6, v7
	v_mul_f32_e32 v6, 0x3c800000, v6
	v_pk_add_f32 v[20:21], v[4:5], v[6:7] op_sel_hi:[1,0] neg_lo:[0,1] neg_hi:[0,1]
	v_pk_add_f32 v[22:23], v[10:11], v[6:7] op_sel_hi:[1,0] neg_lo:[0,1] neg_hi:[0,1]
	v_pk_mul_f32 v[4:5], v[20:21], v[20:21]
	v_pk_mul_f32 v[8:9], v[22:23], v[22:23]
	v_add_f32_e32 v4, v4, v5
	v_pk_add_f32 v[12:13], v[12:13], v[6:7] op_sel_hi:[1,0] neg_lo:[0,1] neg_hi:[0,1]
	v_add_f32_e32 v4, v8, v4
	v_pk_mul_f32 v[10:11], v[12:13], v[12:13]
	v_add_f32_e32 v4, v9, v4
	v_pk_add_f32 v[14:15], v[14:15], v[6:7] op_sel_hi:[1,0] neg_lo:[0,1] neg_hi:[0,1]
	v_add_f32_e32 v4, v10, v4
	v_pk_mul_f32 v[24:25], v[14:15], v[14:15]
	v_add_f32_e32 v4, v11, v4
	v_pk_add_f32 v[16:17], v[16:17], v[6:7] op_sel_hi:[1,0] neg_lo:[0,1] neg_hi:[0,1]
	v_add_f32_e32 v4, v24, v4
	v_pk_add_f32 v[26:27], v[0:1], v[6:7] op_sel_hi:[1,0] neg_lo:[0,1] neg_hi:[0,1]
	v_pk_add_f32 v[28:29], v[2:3], v[6:7] op_sel_hi:[1,0] neg_lo:[0,1] neg_hi:[0,1]
	v_pk_add_f32 v[18:19], v[18:19], v[6:7] op_sel_hi:[1,0] neg_lo:[0,1] neg_hi:[0,1]
	v_pk_mul_f32 v[6:7], v[16:17], v[16:17]
	v_add_f32_e32 v4, v25, v4
	v_add_f32_e32 v4, v6, v4
	v_pk_mul_f32 v[30:31], v[18:19], v[18:19]
	v_add_f32_e32 v4, v7, v4
	v_add_f32_e32 v4, v30, v4
	v_pk_mul_f32 v[0:1], v[26:27], v[26:27]
	v_add_f32_e32 v4, v31, v4
	v_add_f32_e32 v0, v0, v4
	v_pk_mul_f32 v[2:3], v[28:29], v[28:29]
	v_add_f32_e32 v0, v1, v0
	v_add_f32_e32 v0, v2, v0
	v_add_f32_e32 v0, v3, v0
	ds_bpermute_b32 v1, v110, v0
	v_lshlrev_b64 v[30:31], 1, v[192:193]
	s_waitcnt lgkmcnt(0)
	v_add_f32_e32 v0, v0, v1
	ds_bpermute_b32 v1, v111, v0
	v_lshl_add_u64 v[110:111], v[192:193], 2, s[92:93]
	s_waitcnt lgkmcnt(0)
	v_add_f32_e32 v0, v0, v1
	v_fmamk_f32 v0, v0, 0x3c800000, v194
	v_mul_f32_e32 v1, 0x4b800000, v0
	v_cmp_gt_f32_e64 s[68:69], s0, v0
	v_readlane_b32 s0, v253, 0
	s_add_i32 s97, s97, s0
	v_cndmask_b32_e64 v0, v0, v1, s[68:69]
	v_rsq_f32_e32 v0, v0
	s_cmpk_gt_i32 s97, 0x9ff
	v_mul_f32_e32 v1, 0x45800000, v0
	v_cndmask_b32_e64 v24, v0, v1, s[68:69]
	v_lshl_add_u64 v[0:1], s[2:3], 0, v[36:37]
	v_lshl_add_u64 v[36:37], v[0:1], 0, v[30:31]
	global_load_dwordx4 v[0:3], v[36:37], off
	global_load_dwordx4 v[4:7], v[110:111], off
	global_load_dwordx4 v[8:11], v[110:111], off offset:16
	v_readlane_b32 s2, v254, 21
	v_readlane_b32 s3, v254, 22
	s_waitcnt vmcnt(2)
	v_lshlrev_b32_e32 v112, 16, v0
	v_and_b32_e32 v113, 0xffff0000, v0
	v_lshlrev_b32_e32 v114, 16, v1
	v_and_b32_e32 v115, 0xffff0000, v1
	v_lshlrev_b32_e32 v116, 16, v2
	v_and_b32_e32 v117, 0xffff0000, v2
	v_lshlrev_b32_e32 v118, 16, v3
	v_and_b32_e32 v119, 0xffff0000, v3
	v_pk_mul_f32 v[0:1], v[20:21], v[24:25] op_sel_hi:[1,0]
	v_pk_mul_f32 v[2:3], v[22:23], v[24:25] op_sel_hi:[1,0]
	s_waitcnt vmcnt(1)
	v_pk_mul_f32 v[0:1], v[4:5], v[0:1]
	v_pk_mul_f32 v[2:3], v[6:7], v[2:3]
	v_pk_mul_f32 v[0:1], v[0:1], v[112:113]
	v_pk_mul_f32 v[2:3], v[2:3], v[114:115]
	v_cvt_pk_bf16_f32 v0, v0, v1
	v_cvt_pk_bf16_f32 v1, v2, v3
	v_pk_mul_f32 v[2:3], v[12:13], v[24:25] op_sel_hi:[1,0]
	v_pk_mul_f32 v[4:5], v[14:15], v[24:25] op_sel_hi:[1,0]
	s_waitcnt vmcnt(0)
	v_pk_mul_f32 v[2:3], v[8:9], v[2:3]
	v_pk_mul_f32 v[4:5], v[10:11], v[4:5]
	v_lshl_add_u64 v[34:35], s[2:3], 0, v[34:35]
	v_pk_mul_f32 v[2:3], v[2:3], v[116:117]
	v_pk_mul_f32 v[4:5], v[4:5], v[118:119]
	v_lshl_add_u64 v[30:31], v[34:35], 0, v[30:31]
	v_cvt_pk_bf16_f32 v2, v2, v3
	v_cvt_pk_bf16_f32 v3, v4, v5
	global_store_dwordx4 v[30:31], v[0:3], off
	global_load_dwordx4 v[0:3], v[36:37], off offset:64
	s_nop 0
	global_load_dwordx4 v[4:7], v[110:111], off offset:128
	global_load_dwordx4 v[8:11], v[110:111], off offset:144
	v_pk_mul_f32 v[14:15], v[16:17], v[24:25] op_sel_hi:[1,0]
	s_waitcnt vmcnt(2)
	v_lshlrev_b32_e32 v12, 16, v0
	s_waitcnt vmcnt(1)
	v_pk_mul_f32 v[4:5], v[4:5], v[14:15]
	v_and_b32_e32 v13, 0xffff0000, v0
	v_pk_mul_f32 v[4:5], v[4:5], v[12:13]
	v_pk_mul_f32 v[12:13], v[18:19], v[24:25] op_sel_hi:[1,0]
	v_cvt_pk_bf16_f32 v0, v4, v5
	v_lshlrev_b32_e32 v4, 16, v1
	v_pk_mul_f32 v[6:7], v[6:7], v[12:13]
	v_and_b32_e32 v5, 0xffff0000, v1
	v_pk_mul_f32 v[4:5], v[6:7], v[4:5]
	v_pk_mul_f32 v[6:7], v[26:27], v[24:25] op_sel_hi:[1,0]
	v_cvt_pk_bf16_f32 v1, v4, v5
	v_lshlrev_b32_e32 v4, 16, v2
	v_and_b32_e32 v5, 0xffff0000, v2
	s_waitcnt vmcnt(0)
	v_pk_mul_f32 v[6:7], v[8:9], v[6:7]
	s_nop 0
	v_pk_mul_f32 v[4:5], v[6:7], v[4:5]
	v_pk_mul_f32 v[6:7], v[28:29], v[24:25] op_sel_hi:[1,0]
	v_cvt_pk_bf16_f32 v2, v4, v5
	v_lshlrev_b32_e32 v4, 16, v3
	v_and_b32_e32 v5, 0xffff0000, v3
	v_pk_mul_f32 v[6:7], v[10:11], v[6:7]
	s_nop 0
	v_pk_mul_f32 v[4:5], v[6:7], v[4:5]
	s_nop 0
	v_cvt_pk_bf16_f32 v3, v4, v5
	global_store_dwordx4 v[30:31], v[0:3], off offset:64
	s_barrier
	s_cbranch_scc1 .LBB0_873
.LBB0_860:
	s_and_b32 s14, s97, 3
	s_lshl_b32 s4, s97, 5
	s_and_b32 vcc_lo, s4, 0xffffff80
	s_lshl_b32 s0, s14, 6
	v_lshrrev_b32_e32 v0, 3, v33
	v_and_b32_e32 v1, 7, v33
	v_lshlrev_b32_e32 v2, 4, v1
	v_lshl_add_u32 v146, v0, 9, v2
	v_add_u32_e32 v147, 0x8000, v146
	v_mad_u32_u24 v176, v0, s18, v2
	v_and_b32_e32 v3, 32, v0
	v_bfe_u32 v1, v0, 2, 1
	v_lshl_or_b32 v3, v1, 4, v3
	v_bfe_u32 v1, v0, 3, 2
	v_lshl_or_b32 v3, v1, 2, v3
	v_and_b32_e32 v1, 3, v0
	v_or_b32_e32 v3, v3, v1
	v_mul_u32_u24_e32 v3, 0x90, v3
	v_add_u32_e32 v178, v3, v2
	v_lshlrev_b32_e32 v174, 4, v33
	v_add_u32_e32 v175, 0x2000, v174
	v_lshrrev_b32_e32 v0, 4, v33
	v_and_b32_e32 v1, 15, v33
	v_lshlrev_b32_e32 v2, 4, v1
	v_add_u32_e32 v3, s0, v0
	v_mul_u32_u24_e32 v3, 0x28000, v3
	v_add_u32_e32 v172, v3, v2
	v_add_u32_e32 v173, 0x500000, v172
	v_bfe_u32 v1, v0, 2, 1
	v_lshlrev_b32_e32 v3, 4, v1
	v_bfe_u32 v1, v0, 3, 2
	v_lshl_or_b32 v3, v1, 2, v3
	v_and_b32_e32 v1, 3, v0
	v_or_b32_e32 v3, v3, v1
	v_mul_u32_u24_e32 v3, 0x110, v3
	v_add_u32_e32 v177, v3, v2
	v_readlane_b32 s6, v254, 17
	v_readlane_b32 s7, v254, 18
	s_lshl_b32 s4, vcc_lo, 9
	s_lshl_b32 s5, s14, 7
	s_add_u32 s4, s4, s5
	s_add_u32 s6, s6, s4
	s_addc_u32 s7, s7, 0
	v_readlane_b32 s4, v253, 54
	v_readlane_b32 s5, v253, 55
	s_lshl_b32 s8, vcc_lo, 1
	s_add_u32 s4, s4, s8
	s_addc_u32 s5, s5, 0
	v_readlane_b32 s8, v254, 6
	v_readlane_b32 s9, v254, 7
	s_lshl_b32 s15, s97, 14
	s_add_u32 s8, s8, s15
	s_addc_u32 s9, s9, 0
	global_load_dwordx4 v[148:151], v146, s[6:7]
	global_load_dwordx4 v[152:155], v147, s[6:7]
	global_load_dwordx4 v[156:159], v172, s[4:5]
	global_load_dwordx4 v[160:163], v173, s[4:5]
	global_load_dwordx4 v[164:167], v174, s[8:9]
	global_load_dwordx4 v[168:171], v175, s[8:9]
	v_mov_b32_e32 v109, s0
	s_waitcnt vmcnt(0)
	ds_write_b64 v176, v[148:149]
	ds_write_b64 v176, v[150:151] offset:8
	ds_write_b64 v176, v[152:153] offset:8704
	ds_write_b64 v176, v[154:155] offset:8712
	ds_write_b128 v177, v[156:159] offset:17408
	ds_write_b128 v177, v[160:163] offset:26112
	ds_write_b128 v178, v[164:167] offset:34816
	ds_write_b128 v178, v[168:171] offset:44032
	v_mov_b32_e32 v0, s0
	v_mov_b32_e32 v1, 0
	s_branch .Lro_compute
